# baseline (speedup 1.0000x reference)
;   __device__ __forceinline__ int* ctr() const { return (int*)(b + L::o_ctr); }
; template <int G>
; __global__ void __launch_bounds__(256, 2) fwd_kernel(Params P) {
;     ...
;         if (!quiet)
;         for (;;) {
;           __syncthreads();
;           if (tid == 0) s_item = first ? myfirst : nstat + atomicAdd(ctr, 1);
;           first = false;
;           __syncthreads();
;           const int it = s_item;
;           if (it >= nG + nB + nAt) break;
.LBB0_308:
	s_barrier
	s_and_saveexec_b64 s[0:1], s[54:55]
	s_cbranch_execz .LBB0_314
	s_xor_b64 s[10:11], s[10:11], -1
	v_readlane_b32 s2, v252, 57
	s_andn2_b64 vcc, exec, s[10:11]
	v_readlane_b32 s12, v254, 50
	v_readlane_b32 s13, v254, 51
	v_mov_b32_e32 v0, s2
	s_cmp_lt_u32 s2, 32
	s_cbranch_scc1 .Lq_sync
	s_cbranch_vccnz .Lq_issue
	s_waitcnt vmcnt(0)
	v_readlane_b32 s10, v252, 54
	s_nop 1
	v_add_u32_e32 v0, s10, v251
.Lq_issue:
	v_mov_b32_e32 v251, 1
	s_nop 4
	global_atomic_add v251, v153, v251, s[12:13] sc0
	s_branch .LBB0_313
.Lq_sync:
	s_cbranch_vccnz .LBB0_313
	v_mov_b32_e32 v1, 1
	s_nop 4
	global_atomic_add v1, v153, v1, s[12:13] sc0
	s_waitcnt vmcnt(0)
	v_readlane_b32 s10, v252, 54
	s_nop 1
	v_add_u32_e32 v0, s10, v1
